# previous + XCD groups start layer work staggered by g x ~3.5 us after the first barrier (persists because later barriers are XCD-local)
# speedup vs baseline: 1.0103x; 1.0103x over previous
; __device__ __forceinline__ void xcd_barrier(const XcdBarrier& b) {
;     ...
;     __syncthreads();
; __global__ void __launch_bounds__(NWAVES * 64, 2) fwd_kernel(Args args) {
;     ...
;         if (ph + 1 < args.ph_hi || rep + 1 < nrep) { if (args.ph_hi > 1000) grid.sync(); else xcd_barrier(xb); } else __syncthreads();
.LBB0_486:
	s_or_b64 exec, exec, s[26:27]
	s_cmp_eq_u32 s10, 1
	s_cbranch_scc0 stg_skip
	s_and_b32 s2, s89, 7
stg_loop:
	s_cmp_eq_u32 s2, 0
	s_cbranch_scc1 stg_skip
	s_sleep 127
	s_sub_u32 s2, s2, 1
	s_branch stg_loop
stg_skip:
	s_mov_b64 s[26:27], 0
	s_waitcnt lgkmcnt(0)
	s_barrier
